# Up0/Up1: half of the CUs (blockIdx bit 3) start the GEMM phase ~3.4 us later (s_sleep 127) to de-phase the epilogue store bursts, on v49
# baseline (speedup 1.0000x reference)
;     __host__ __device__ bool next(int i, Unit& u) const {
;         const long L = (long)i * G + c; if (L >= nwg) return false;
;         int wgid = (int)L; { const int q = nwg / NXCD, r = nwg % NXCD, xcd = wgid % NXCD, off = wgid / NXCD; wgid = (xcd < r ? xcd * (q + 1) : r * (q + 1) + (xcd - r) * q) + off; }
;         const int nig = WGM * nN, gid = wgid / nig, fm = gid * WGM, gsz = (nM - fm) < WGM ? (nM - fm) : WGM;
;         u.pm = fm + ((wgid % nig) % gsz); u.pn = (wgid % nig) / gsz; return true;
.LBB0_1454:
	s_or_b64 exec, exec, s[2:3]
	v_cmp_gt_i32_e32 vcc, 6, v1
	v_cmp_lt_i32_e64 s[2:3], 5, v5
	s_and_b64 s[0:1], vcc, s[2:3]
	s_and_saveexec_b64 s[4:5], s[0:1]
	s_cbranch_execz .LBB0_1479
	v_and_b32_e32 v10, 0x3ff, v0
	s_cmpk_gt_i32 s33, 0x7ff
	v_readfirstlane_b32 s0, v10
	s_cbranch_scc1 .LBB0_1479
	s_bitcmp1_b32 s33, 3
	s_cbranch_scc0 .Lstag_u0
	s_sleep 127
.Lstag_u0:
	s_ashr_i32 s38, s33, 31
	s_lshr_b32 s1, s38, 29
	s_add_i32 s1, s33, s1
	s_and_b32 s2, s1, -8
	s_sub_i32 s7, s33, s2
	s_cmp_gt_i32 s7, -1
	s_cbranch_scc0 .LBB0_1458
	s_lshl_b32 s6, s7, 8
	s_cbranch_execz .LBB0_1459
	s_branch .LBB0_1460

;     __host__ __device__ bool next(int i, Unit& u) const {
;         const long L = (long)i * G + c; if (L >= nwg) return false;
;         int wgid = (int)L; { const int q = nwg / NXCD, r = nwg % NXCD, xcd = wgid % NXCD, off = wgid / NXCD; wgid = (xcd < r ? xcd * (q + 1) : r * (q + 1) + (xcd - r) * q) + off; }
;         const int nig = WGM * nN, gid = wgid / nig, fm = gid * WGM, gsz = (nM - fm) < WGM ? (nM - fm) : WGM;
;         u.pm = fm + ((wgid % nig) % gsz); u.pn = (wgid % nig) / gsz; return true;
.LBB0_3705:
	s_or_b64 exec, exec, s[2:3]
	v_cmp_gt_i32_e32 vcc, 13, v1
	v_cmp_lt_i32_e64 s[2:3], 12, v5
	s_and_b64 s[0:1], vcc, s[2:3]
	s_and_saveexec_b64 s[4:5], s[0:1]
	s_cbranch_execz .LBB0_3730
	v_and_b32_e32 v10, 0x3ff, v0
	s_cmpk_gt_i32 s33, 0x7ff
	v_readfirstlane_b32 s0, v10
	s_cbranch_scc1 .LBB0_3730
	s_bitcmp1_b32 s33, 3
	s_cbranch_scc0 .Lstag_u1
	s_sleep 127
